# attention A loop: dead has-more flag math removed, single vmcnt wait before the staging LDS writes
# baseline (speedup 1.0000x reference)
; #define FLAS __attribute__((address_space(3)))
; __device__ __forceinline__ void attn_unit_a(FLAS unsigned char* lds, const Unit u) {
;     ...
;         if (i + 2 < NT) { kreg = *(const u32x4*)(ksrc + (size_t)(u.t_lo + i + 2) * 64 * u.ldk);
; #pragma unroll
;             for (int j = 0; j < 2; ++j) vreg[j] = *(const u32x4*)(vsrc + (size_t)j * 64 * MTOK + (u.t_lo + i + 2) * 64); }
;         const int vsp = (i == 0) ? 0 : ((i - 1) & 3);
;         const FLAS unsigned char* vb_ = lds + LA_V + vsp * VBUF + r32 * VPITCH + hi * 16;
;         const FLAS unsigned char* kb = lds + LA_K + ((i + 1) & 1) * KBUF;
.LBB0_435:
	s_cmpk_gt_u32 s19, 0x7d
	s_cselect_b64 s[4:5], -1, 0
	s_xor_b64 s[20:21], s[24:25], -1
	s_waitcnt lgkmcnt(1)
	v_mfma_f32_32x32x16_bf16 v[48:63], v[128:131], v[204:207], v[48:63]
	ds_read_b128 v[128:131], v200 offset:30208
	s_and_b64 vcc, exec, s[4:5]
	s_cbranch_vccnz .LBB0_437
	global_load_dwordx4 v[176:179], v230, s[50:51]
	global_load_dwordx4 v[180:183], v228, s[52:53] offset:256
	global_load_dwordx4 v[184:187], v229, s[52:53] offset:256

; #define FLAS __attribute__((address_space(3)))
; #define FA_SB() __builtin_amdgcn_sched_barrier(0)
; #define FA_EXP2(J, PX, R) do { const float e0_ = __builtin_amdgcn_exp2f(PX[R]), e1_ = __builtin_amdgcn_exp2f(PX[(R) + 1]); ps += e0_; ps += e1_; PWN[(J) >> 2][(J) & 3] = cvtpk(e0_, e1_); } while (0)
; __device__ __forceinline__ void attn_unit_a(FLAS unsigned char* lds, const Unit u) {
;     ...
;         if (ziN) { pN0 = __builtin_amdgcn_mfma_f32_32x32x16_bf16(kf[0], qr[0], z16, 0, 0, 0); FA_EXP2(8, pC1, 0); FA_SB(); pN1 = __builtin_amdgcn_mfma_f32_32x32x16_bf16(kf[1], qr[0], z16, 0, 0, 0); }
;         else { pN0 = __builtin_amdgcn_mfma_f32_32x32x16_bf16(kf[0], qr[0], pN0, 0, 0, 0); FA_EXP2(8, pC1, 0); FA_SB(); pN1 = __builtin_amdgcn_mfma_f32_32x32x16_bf16(kf[1], qr[0], pN1, 0, 0, 0); }
;         kf[0] = FA_KF(2, 0); kf[1] = FA_KF(2, 1); FA_EXP2(9, pC1, 2); FA_SB();
;         pN0 = __builtin_amdgcn_mfma_f32_32x32x16_bf16(kf[2], qr[1], pN0, 0, 0, 0); FA_EXP2(10, pC1, 4); FA_SB();
;         pN1 = __builtin_amdgcn_mfma_f32_32x32x16_bf16(kf[3], qr[1], pN1, 0, 0, 0); kf[2] = FA_KF(3, 0); kf[3] = FA_KF(3, 1); FA_EXP2(11, pC1, 6); FA_SB();
;         pN0 = __builtin_amdgcn_mfma_f32_32x32x16_bf16(kf[0], qr[2], pN0, 0, 0, 0); FA_EXP2(12, pC1, 8); FA_SB();
;         pN1 = __builtin_amdgcn_mfma_f32_32x32x16_bf16(kf[1], qr[2], pN1, 0, 0, 0); FA_EXP2(13, pC1, 10); FA_SB();
;         pN0 = __builtin_amdgcn_mfma_f32_32x32x16_bf16(kf[2], qr[3], pN0, 0, 0, 0); FA_EXP2(14, pC1, 12); FA_SB();
;         pN1 = __builtin_amdgcn_mfma_f32_32x32x16_bf16(kf[3], qr[3], pN1, 0, 0, 0); FA_EXP2(15, pC1, 14); FA_SB();
;     ...
;         lsum += ps; cbC = cbN;
;         if (i + 2 < NT) { *(FLAS u32x4*)(lds + LA_K + (i & 1) * KBUF + kdst) = kreg;
; #pragma unroll
;             for (int j = 0; j < 2; ++j) { *(FLAS u32x2*)(lds + LA_V + ((i + 2) & 3) * VBUF + vdst + j * 64 * VPITCH) = (u32x2){vreg[j].x, vreg[j].y}; *(FLAS u32x2*)(lds + LA_V + ((i + 2) & 3) * VBUF + vdst + j * 64 * VPITCH + 16) = (u32x2){vreg[j].z, vreg[j].w}; } }
.Lk2_e:
	ds_read_b128 v[128:131], v249 offset:8192
	ds_read_b128 v[132:135], v249 offset:8704
	s_add_i32 s34, s19, 2
	v_mfma_f32_32x32x16_bf16 v[64:79], v[196:199], v[164:167], v[64:79]
	v_exp_f32_e32 v116, v116
	v_exp_f32_e32 v117, v117
	v_mfma_f32_32x32x16_bf16 v[80:95], v[192:195], v[164:167], v[80:95]
	ds_read_b128 v[136:139], v250 offset:8192
	ds_read_b128 v[140:143], v250 offset:8704
	s_and_b32 s0, s34, 2
	s_mulk_i32 s0, 0x4800
	v_add_u32_e32 v188, s0, v245
	v_add_u32_e32 v189, 0x4000, v188
	v_add_u32_e32 v188, 0x6000, v188
	s_waitcnt vmcnt(0)
	ds_write_b128 v225, v[176:179]
	ds_write2_b64 v189, v[180:181], v[182:183] offset1:2
	ds_write2_b64 v188, v[184:185], v[186:187] offset0:128 offset1:130
	v_exp_f32_e32 v118, v118
	v_exp_f32_e32 v119, v119
	s_and_b32 s0, s19, 2
	s_mulk_i32 s0, 0x4800
	v_add_u32_e32 v201, s0, v251
	s_waitcnt lgkmcnt(5)
	v_mfma_f32_32x32x16_bf16 v[64:79], v[128:131], v[168:171], v[64:79]
	ds_read_b128 v[128:131], v201 offset:16384
	v_exp_f32_e32 v120, v120
	v_exp_f32_e32 v121, v121
	v_mfma_f32_32x32x16_bf16 v[80:95], v[132:135], v[168:171], v[80:95]
	ds_read_b128 v[132:135], v201 offset:20992
	v_exp_f32_e32 v122, v122
	v_exp_f32_e32 v123, v123
	s_waitcnt lgkmcnt(5)
	v_mfma_f32_32x32x16_bf16 v[64:79], v[136:139], v[172:175], v[64:79]
	ds_read_b128 v[136:139], v201 offset:25600
	v_exp_f32_e32 v124, v124
	v_exp_f32_e32 v125, v125
	v_mfma_f32_32x32x16_bf16 v[80:95], v[140:143], v[172:175], v[80:95]
	v_exp_f32_e32 v126, v126
	v_exp_f32_e32 v127, v127
	v_cvt_pk_bf16_f32 v140, v96, v97
	v_cvt_pk_bf16_f32 v141, v98, v99
	v_cvt_pk_bf16_f32 v142, v100, v101
	v_cvt_pk_bf16_f32 v143, v102, v103

; #define FLAS __attribute__((address_space(3)))
; __device__ __forceinline__ void attn_unit_a(FLAS unsigned char* lds, const Unit u) {
;     ...
;         if (i + 2 < NT) { kreg = *(const u32x4*)(ksrc + (size_t)(u.t_lo + i + 2) * 64 * u.ldk);
; #pragma unroll
;             for (int j = 0; j < 2; ++j) vreg[j] = *(const u32x4*)(vsrc + (size_t)j * 64 * MTOK + (u.t_lo + i + 2) * 64); }
;         const int vsp = (i == 0) ? 0 : ((i - 1) & 3);
;         const FLAS unsigned char* vb_ = lds + LA_V + vsp * VBUF + r32 * VPITCH + hi * 16;
;         const FLAS unsigned char* kb = lds + LA_K + ((i + 1) & 1) * KBUF;
.LBB0_458:
	s_waitcnt lgkmcnt(1)
	v_mfma_f32_32x32x16_bf16 v[48:63], v[128:131], v[140:143], v[48:63]
	ds_read_b128 v[128:131], v201 offset:30208
	s_cmpk_gt_u32 s19, 0x7c
	s_cbranch_scc1 .LBB0_460
	global_load_dwordx4 v[176:179], v231, s[50:51]
	global_load_dwordx4 v[180:183], v228, s[52:53] offset:384
	global_load_dwordx4 v[184:187], v229, s[52:53] offset:384

; #define FLAS __attribute__((address_space(3)))
; #define FA_SB() __builtin_amdgcn_sched_barrier(0)
; #define FA_EXP2(J, PX, R) do { const float e0_ = __builtin_amdgcn_exp2f(PX[R]), e1_ = __builtin_amdgcn_exp2f(PX[(R) + 1]); ps += e0_; ps += e1_; PWN[(J) >> 2][(J) & 3] = cvtpk(e0_, e1_); } while (0)
; __device__ __forceinline__ void attn_unit_a(FLAS unsigned char* lds, const Unit u) {
;     ...
;         if (ziN) { pN0 = __builtin_amdgcn_mfma_f32_32x32x16_bf16(kf[0], qr[0], z16, 0, 0, 0); FA_EXP2(8, pC1, 0); FA_SB(); pN1 = __builtin_amdgcn_mfma_f32_32x32x16_bf16(kf[1], qr[0], z16, 0, 0, 0); }
;         else { pN0 = __builtin_amdgcn_mfma_f32_32x32x16_bf16(kf[0], qr[0], pN0, 0, 0, 0); FA_EXP2(8, pC1, 0); FA_SB(); pN1 = __builtin_amdgcn_mfma_f32_32x32x16_bf16(kf[1], qr[0], pN1, 0, 0, 0); }
;         kf[0] = FA_KF(2, 0); kf[1] = FA_KF(2, 1); FA_EXP2(9, pC1, 2); FA_SB();
;         pN0 = __builtin_amdgcn_mfma_f32_32x32x16_bf16(kf[2], qr[1], pN0, 0, 0, 0); FA_EXP2(10, pC1, 4); FA_SB();
;         pN1 = __builtin_amdgcn_mfma_f32_32x32x16_bf16(kf[3], qr[1], pN1, 0, 0, 0); kf[2] = FA_KF(3, 0); kf[3] = FA_KF(3, 1); FA_EXP2(11, pC1, 6); FA_SB();
;         pN0 = __builtin_amdgcn_mfma_f32_32x32x16_bf16(kf[0], qr[2], pN0, 0, 0, 0); FA_EXP2(12, pC1, 8); FA_SB();
;         pN1 = __builtin_amdgcn_mfma_f32_32x32x16_bf16(kf[1], qr[2], pN1, 0, 0, 0); FA_EXP2(13, pC1, 10); FA_SB();
;         pN0 = __builtin_amdgcn_mfma_f32_32x32x16_bf16(kf[2], qr[3], pN0, 0, 0, 0); FA_EXP2(14, pC1, 12); FA_SB();
;         pN1 = __builtin_amdgcn_mfma_f32_32x32x16_bf16(kf[3], qr[3], pN1, 0, 0, 0); FA_EXP2(15, pC1, 14); FA_SB();
;     ...
;         lsum += ps; cbC = cbN;
;         if (i + 2 < NT) { *(FLAS u32x4*)(lds + LA_K + (i & 1) * KBUF + kdst) = kreg;
; #pragma unroll
;             for (int j = 0; j < 2; ++j) { *(FLAS u32x2*)(lds + LA_V + ((i + 2) & 3) * VBUF + vdst + j * 64 * VPITCH) = (u32x2){vreg[j].x, vreg[j].y}; *(FLAS u32x2*)(lds + LA_V + ((i + 2) & 3) * VBUF + vdst + j * 64 * VPITCH + 16) = (u32x2){vreg[j].z, vreg[j].w}; } }
.Lk2_o:
	ds_read_b128 v[128:131], v249
	ds_read_b128 v[132:135], v249 offset:512
	v_mfma_f32_32x32x16_bf16 v[96:111], v[192:195], v[164:167], v[96:111]
	v_exp_f32_e32 v84, v84
	v_exp_f32_e32 v85, v85
	v_mfma_f32_32x32x16_bf16 v[112:127], v[188:191], v[164:167], v[112:127]
	ds_read_b128 v[136:139], v250
	ds_read_b128 v[140:143], v250 offset:512
	v_add_u32_e32 v204, s18, v245
	v_add_u32_e32 v205, 0x4000, v204
	v_add_u32_e32 v204, 0x6000, v204
	s_waitcnt vmcnt(0)
	ds_write_b128 v225, v[176:179] offset:8192
	ds_write2_b64 v205, v[180:181], v[182:183] offset1:2
	ds_write2_b64 v204, v[184:185], v[186:187] offset0:128 offset1:130
	v_exp_f32_e32 v86, v86
	v_exp_f32_e32 v87, v87
	s_add_i32 s12, s34, -1
	s_and_b32 s18, s12, 3
	s_mulk_i32 s18, 0x4800
	v_add_u32_e32 v200, s18, v251
	s_waitcnt lgkmcnt(5)
	v_mfma_f32_32x32x16_bf16 v[96:111], v[128:131], v[168:171], v[96:111]
	ds_read_b128 v[128:131], v200 offset:16384
	v_exp_f32_e32 v88, v88
	v_exp_f32_e32 v89, v89
	v_mfma_f32_32x32x16_bf16 v[112:127], v[132:135], v[168:171], v[112:127]
	ds_read_b128 v[132:135], v200 offset:20992
	v_exp_f32_e32 v90, v90
	v_exp_f32_e32 v91, v91
	s_waitcnt lgkmcnt(5)
	v_mfma_f32_32x32x16_bf16 v[96:111], v[136:139], v[172:175], v[96:111]
	ds_read_b128 v[136:139], v200 offset:25600
	v_exp_f32_e32 v92, v92
	v_exp_f32_e32 v93, v93
	v_mfma_f32_32x32x16_bf16 v[112:127], v[140:143], v[172:175], v[112:127]
	v_exp_f32_e32 v94, v94
	v_exp_f32_e32 v95, v95
